# ph3: blocks 256..511 run attention before scan2 so the memory-bound scan2 of one co-resident block overlaps the other's attention
# baseline (speedup 1.0000x reference)
; #define KARGP(z_) ((const P*)(const void*)((const __attribute__((address_space(4))) char*)__builtin_amdgcn_kernarg_segment_ptr() + (z_)))
; __global__ void __launch_bounds__(NTHR, 2) mega(P p) {
;     ...
;       case 3: {
;         OPAQUE_Z; const P& q = *KARGP(zz);
;         ph_scan2(q);
;         ph_attn(q, need_ctx, smem);
;         break;
.LBB0_1225:
	v_readlane_b32 s2, v254, 22
	s_cmp_gt_i32 s2, 0
	s_mov_b64 s[2:3], -1
	s_cbranch_scc0 .LBB0_1453
	v_readlane_b32 s0, v254, 22
	s_cmp_lt_i32 s0, 2
	s_mov_b64 s[0:1], -1
	s_cbranch_scc1 .LBB0_1371
	v_readlane_b32 s0, v254, 22
	s_cmp_gt_i32 s0, 2
	s_mov_b64 s[0:1], -1
	s_cbranch_scc0 .LBB0_1263
	s_cmp_lt_u32 s87, 0x100
	s_cbranch_scc1 .Lro_norm
	v_writelane_b32 v255, 1, 62
	s_mov_b64 s[6:7], exec
	s_load_dwordx2 s[2:3], s[88:89], 0x118
	s_branch .LBB0_1239
.Lro_norm:
	v_writelane_b32 v255, 0, 62
.Lro_scan2:
	s_mov_b32 s0, 0
	s_ashr_i32 s1, s0, 31
	s_add_u32 s0, s88, s0
	s_addc_u32 s1, s89, s1
	s_load_dwordx2 s[2:3], s[0:1], 0x118
	s_mov_b32 s0, 0
	s_add_i32 s1, s0, s87
	s_lshl_b32 s1, s1, 8
	s_add_i32 s1, s1, s0
	s_waitcnt vmcnt(15)
	v_add_u32_e32 v3, s1, v128
	s_mov_b32 s1, 0xc0000
	v_cmp_gt_i32_e32 vcc, s1, v3
	s_and_saveexec_b64 s[6:7], vcc
	s_cbranch_execz .LBB0_1239
	s_ashr_i32 s1, s0, 31
	s_waitcnt lgkmcnt(0)
	s_add_u32 s4, s2, s0
	s_addc_u32 s1, s3, s1
	s_add_u32 s8, s4, 0x23ad9000
	s_addc_u32 s9, s1, 0
	s_add_u32 s10, s4, 0x2a725800
	s_addc_u32 s11, s1, 0
	s_add_u32 s12, s4, 0x2a6d9000
	s_addc_u32 s13, s1, 0
	s_add_i32 s0, s0, s90
	s_lshl_b32 s20, s0, 8
	s_mov_b64 s[14:15], 0

; #define KARGP(z_) ((const P*)(const void*)((const __attribute__((address_space(4))) char*)__builtin_amdgcn_kernarg_segment_ptr() + (z_)))
; __device__ __forceinline__ void ph_attn(const P& p, int need_ctx, char* smem) {
;     ...
;   int ntask = 8 * 4 * 16 + (need_ctx ? 8 * 4 * 2 : 0);
;   for (int task = (blockIdx.x + zz); task < ntask; task += (gridDim.x + zz)) {
; __global__ void __launch_bounds__(NTHR, 2) mega(P p) {
;     ...
;         OPAQUE_Z; const P& q = *KARGP(zz);
;         ph_scan2(q);
;         ph_attn(q, need_ctx, smem);
;         break;
.LBB0_1239:
	s_or_b64 exec, exec, s[6:7]
	v_readlane_b32 s0, v255, 62
	s_cmp_eq_u32 s0, 2
	s_cbranch_scc1 .LBB0_1262
	s_and_b64 s[0:1], s[40:41], exec
	s_movk_i32 s0, 0x200
	s_mov_b32 s20, 0
	s_cselect_b32 s16, 0x200, s0
	s_add_i32 s17, s20, s87
	v_mov_b32_e32 v196, 0x80
	s_cmp_ge_i32 s17, s16
	s_cbranch_scc1 .LBB0_1262

; #define KARGP(z_) ((const P*)(const void*)((const __attribute__((address_space(4))) char*)__builtin_amdgcn_kernarg_segment_ptr() + (z_)))
; __global__ void __launch_bounds__(NTHR, 2) mega(P p) {
;     ...
;       case 3: {
;         OPAQUE_Z; const P& q = *KARGP(zz);
;         ph_scan2(q);
;         ph_attn(q, need_ctx, smem);
;         break;
.LBB0_1262:
	v_mov_b32_e32 v126, v196
	v_readlane_b32 s0, v255, 62
	s_cmp_eq_u32 s0, 1
	s_cbranch_scc0 .Lro_exit
	v_writelane_b32 v255, 2, 62
	s_branch .Lro_scan2
.Lro_exit:
	s_mov_b64 s[0:1], 0
.LBB0_1263:
	s_and_b64 vcc, exec, s[0:1]
	s_cbranch_vccz .LBB0_1370
	s_mov_b32 s0, 0
	s_mov_b32 s39, 0
	s_add_i32 s36, s39, s87
	s_cmpk_gt_i32 s36, 0xd7f
	s_cbranch_scc1 .LBB0_1370
	s_ashr_i32 s1, s0, 31
	s_add_u32 s0, s88, s0
	s_addc_u32 s1, s89, s1
	s_waitcnt lgkmcnt(0)
	s_load_dwordx2 s[2:3], s[0:1], 0x118
	s_ashr_i32 s1, s39, 31
	s_waitcnt vmcnt(8)
	v_add_u32_e32 v40, s39, v128
	v_ashrrev_i32_e32 v41, 31, v40
	v_and_b32_e32 v49, 63, v40
	s_waitcnt lgkmcnt(0)
	s_add_u32 s0, s2, s39
	s_addc_u32 s1, s3, s1
	s_add_u32 s37, s0, 0x23ad9000
	s_addc_u32 s38, s1, 0
	v_lshl_add_u64 v[0:1], v[40:41], 2, s[0:1]
	s_mov_b64 s[0:1], 0x2a6d9000
	v_ashrrev_i32_e32 v43, 6, v40
	s_waitcnt vmcnt(0)
	v_lshl_add_u64 v[44:45], v[0:1], 0, s[0:1]
	v_lshlrev_b32_e32 v58, 2, v49
	v_lshlrev_b32_e32 v0, 1, v49
	v_sub_u32_e32 v46, v58, v0
	v_lshlrev_b32_e32 v0, 4, v43
	v_and_b32_e32 v47, 15, v40
	v_bfe_u32 v2, v40, 4, 2
	v_and_b32_e32 v0, 48, v0
	v_add_u32_e32 v51, 0x100, v40
	v_or_b32_e32 v1, v0, v47
	v_lshl_or_b32 v60, v2, 2, v0
	v_sub_u32_e32 v0, 0, v40
	v_add_u32_e32 v53, 0x200, v40
	v_max_i32_e32 v48, v40, v0
	v_sub_u32_e32 v0, 0, v51
	v_add_u32_e32 v55, 0x300, v40
	v_max_i32_e32 v50, v51, v0
	v_sub_u32_e32 v0, 0, v53
	v_lshlrev_b32_e32 v42, 4, v2
	v_mul_u32_u24_e32 v1, 0x90, v1
	v_max_i32_e32 v52, v53, v0
	v_sub_u32_e32 v0, 0, v55
	v_lshlrev_b32_e32 v59, 7, v49
	s_add_i32 s39, s39, s90
	v_ashrrev_i32_e32 v61, 31, v51
	v_ashrrev_i32_e32 v62, 31, v53
	v_ashrrev_i32_e32 v63, 31, v55
	v_max_i32_e32 v54, v55, v0
	v_lshlrev_b32_e32 v64, 2, v43
	v_add_u32_e32 v65, v42, v1
	s_branch .LBB0_1267
